# NA local-stage bias: 16 serialized LDS lookups (wait+branch each) replaced by one batched read group + straight-line fmac/cndmask
# speedup vs baseline: 1.0198x; 1.0184x over previous
.LBB0_412:
	s_and_b32 s88, s2, 0x4000
	v_add_u32_e32 v46, s88, v76
	v_add_u32_e32 v0, v46, v73
	ds_read_b128 v[26:29], v0
	ds_read_b128 v[30:33], v0 offset:2048
	ds_read_b128 v[34:37], v0 offset:4096
	ds_read_b128 v[38:41], v0 offset:6144
	s_add_i32 s88, s1, s81
	s_add_i32 s89, s81, 0xe40
	v_add_u32_e32 v47, s90, v69
	v_add_u32_e32 v93, v46, v70
	s_and_b64 s[38:39], s[38:39], exec
	s_waitcnt vmcnt(1) lgkmcnt(2)
	v_mfma_f32_16x16x32_bf16 v[42:45], v[30:33], v[22:25], 0
	ds_read_b128 v[30:33], v93
	v_add_u32_e32 v46, 32, v47
	s_cselect_b32 s38, s88, s89
	s_waitcnt lgkmcnt(1)
	v_mfma_f32_16x16x32_bf16 v[94:97], v[38:41], v[22:25], 0
	ds_read_b128 v[38:41], v93 offset:2048
	v_mad_i64_i32 v[50:51], s[88:89], v47, s92, v[64:65]
	v_mad_i64_i32 v[52:53], s[88:89], v46, s92, v[64:65]
	ds_read_b128 v[46:49], v93 offset:4096
	v_mfma_f32_16x16x32_bf16 v[26:29], v[26:29], v[22:25], 0
	s_ashr_i32 s39, s38, 31
	v_lshl_add_u64 v[98:99], s[38:39], 1, v[66:67]
	s_cmp_lt_u32 s0, 8
	v_mfma_f32_16x16x32_bf16 v[34:37], v[34:37], v[22:25], 0
	s_cselect_b64 s[88:89], -1, 0
	s_cmp_gt_u32 s0, 7
	s_waitcnt vmcnt(0) lgkmcnt(2)
	v_mfma_f32_16x16x32_bf16 v[54:57], v[30:33], v[18:21], v[26:29]
	s_nop 2
	global_load_dwordx4 v[26:29], v[50:51], off
	global_load_dwordx4 v[30:33], v[52:53], off
	s_nop 2
	v_mul_f32_e32 v54, 0x3e38aa3b, v54
	s_waitcnt lgkmcnt(1)
	v_mfma_f32_16x16x32_bf16 v[50:53], v[38:41], v[18:21], v[42:45]
	v_lshl_add_u64 v[38:39], v[98:99], 0, v[60:61]
	v_lshl_add_u64 v[40:41], v[98:99], 0, v[62:63]
	s_nop 0
	ds_read_b128 v[42:45], v93 offset:6144
	s_waitcnt lgkmcnt(1)
	v_mfma_f32_16x16x32_bf16 v[46:49], v[46:49], v[18:21], v[34:37]
	s_nop 2
	global_load_dwordx4 v[34:37], v[38:39], off
	s_nop 0
	global_load_dwordx4 v[38:41], v[40:41], off
	s_waitcnt lgkmcnt(0)
	v_mfma_f32_16x16x32_bf16 v[42:45], v[42:45], v[18:21], v[94:97]
	s_cbranch_scc1 .Lna_ctxstage
	v_add_u32_e32 v100, s80, v92
	ds_read_b32 v100, v100 offset:1364
	v_add_u32_e32 v101, s80, v91
	ds_read_b32 v101, v101 offset:1364
	v_add_u32_e32 v102, s80, v90
	ds_read_b32 v102, v102 offset:1364
	v_add_u32_e32 v103, s80, v89
	ds_read_b32 v103, v103 offset:1364
	v_add_u32_e32 v104, s80, v88
	ds_read_b32 v104, v104 offset:1364
	v_add_u32_e32 v105, s80, v87
	ds_read_b32 v105, v105 offset:1364
	v_add_u32_e32 v106, s80, v86
	ds_read_b32 v106, v106 offset:1364
	v_add_u32_e32 v107, s80, v85
	ds_read_b32 v107, v107 offset:1364
	v_add_u32_e32 v108, s80, v84
	ds_read_b32 v108, v108 offset:1364
	v_add_u32_e32 v109, s80, v83
	ds_read_b32 v109, v109 offset:1364
	v_add_u32_e32 v110, s80, v82
	ds_read_b32 v110, v110 offset:1364
	v_add_u32_e32 v111, s80, v81
	ds_read_b32 v111, v111 offset:1364
	v_add_u32_e32 v112, s80, v80
	ds_read_b32 v112, v112 offset:1364
	v_add_u32_e32 v113, s80, v79
	ds_read_b32 v113, v113 offset:1364
	v_add_u32_e32 v114, s80, v78
	ds_read_b32 v114, v114 offset:1364
	v_add_u32_e32 v115, s80, v77
	ds_read_b32 v115, v115 offset:1364
	v_mul_f32_e32 v55, 0x3e38aa3b, v55
	v_mul_f32_e32 v56, 0x3e38aa3b, v56
	v_mul_f32_e32 v57, 0x3e38aa3b, v57
	v_mul_f32_e32 v50, 0x3e38aa3b, v50
	v_mul_f32_e32 v51, 0x3e38aa3b, v51
	v_mul_f32_e32 v52, 0x3e38aa3b, v52
	v_mul_f32_e32 v53, 0x3e38aa3b, v53
	v_mul_f32_e32 v46, 0x3e38aa3b, v46
	v_mul_f32_e32 v47, 0x3e38aa3b, v47
	v_mul_f32_e32 v48, 0x3e38aa3b, v48
	v_mul_f32_e32 v49, 0x3e38aa3b, v49
	v_mul_f32_e32 v42, 0x3e38aa3b, v42
	v_mul_f32_e32 v43, 0x3e38aa3b, v43
	v_mul_f32_e32 v44, 0x3e38aa3b, v44
	v_mul_f32_e32 v45, 0x3e38aa3b, v45
	s_waitcnt lgkmcnt(0)
	v_fmac_f32_e32 v54, 0x3fb8aa3b, v100
	v_fmac_f32_e32 v55, 0x3fb8aa3b, v101
	v_fmac_f32_e32 v56, 0x3fb8aa3b, v102
	v_fmac_f32_e32 v57, 0x3fb8aa3b, v103
	v_fmac_f32_e32 v50, 0x3fb8aa3b, v104
	v_fmac_f32_e32 v51, 0x3fb8aa3b, v105
	v_fmac_f32_e32 v52, 0x3fb8aa3b, v106
	v_fmac_f32_e32 v53, 0x3fb8aa3b, v107
	v_fmac_f32_e32 v46, 0x3fb8aa3b, v108
	v_fmac_f32_e32 v47, 0x3fb8aa3b, v109
	v_fmac_f32_e32 v48, 0x3fb8aa3b, v110
	v_fmac_f32_e32 v49, 0x3fb8aa3b, v111
	v_fmac_f32_e32 v42, 0x3fb8aa3b, v112
	v_fmac_f32_e32 v43, 0x3fb8aa3b, v113
	v_fmac_f32_e32 v44, 0x3fb8aa3b, v114
	v_fmac_f32_e32 v45, 0x3fb8aa3b, v115
	v_cndmask_b32_e64 v54, v54, v221, s[4:5]
	v_cndmask_b32_e64 v55, v55, v221, s[6:7]
	v_cndmask_b32_e64 v56, v56, v221, s[8:9]
	v_cndmask_b32_e64 v57, v57, v221, s[10:11]
	v_cndmask_b32_e64 v50, v221, v50, s[12:13]
	v_cndmask_b32_e64 v51, v221, v51, s[14:15]
	v_cndmask_b32_e64 v52, v221, v52, s[16:17]
	v_cndmask_b32_e64 v53, v221, v53, s[18:19]
	v_cndmask_b32_e64 v46, v221, v46, s[20:21]
	v_cndmask_b32_e64 v47, v221, v47, s[22:23]
	v_cndmask_b32_e64 v48, v221, v48, s[24:25]
	v_cndmask_b32_e64 v49, v221, v49, s[26:27]
	v_cndmask_b32_e64 v42, v221, v42, s[28:29]
	v_cndmask_b32_e64 v43, v221, v43, s[30:31]
	v_cndmask_b32_e64 v44, v221, v44, s[34:35]
	v_cndmask_b32_e64 v45, v221, v45, s[36:37]
	s_branch .LBB0_430
.Lna_ctxstage:
	v_mul_f32_e32 v55, 0x3e38aa3b, v55
	v_mul_f32_e32 v56, 0x3e38aa3b, v56
	v_mul_f32_e32 v57, 0x3e38aa3b, v57
	v_mul_f32_e32 v50, 0x3e38aa3b, v50
	v_mul_f32_e32 v51, 0x3e38aa3b, v51
	v_mul_f32_e32 v52, 0x3e38aa3b, v52
	v_mul_f32_e32 v53, 0x3e38aa3b, v53
	v_mul_f32_e32 v46, 0x3e38aa3b, v46
	v_mul_f32_e32 v47, 0x3e38aa3b, v47
	v_mul_f32_e32 v48, 0x3e38aa3b, v48
	v_mul_f32_e32 v49, 0x3e38aa3b, v49
	v_mul_f32_e32 v42, 0x3e38aa3b, v42
	v_mul_f32_e32 v43, 0x3e38aa3b, v43
	v_mul_f32_e32 v44, 0x3e38aa3b, v44
	v_mul_f32_e32 v45, 0x3e38aa3b, v45

.LBB0_432:
	v_sub_f32_e32 v54, v54, v71
	v_sub_f32_e32 v55, v55, v71
	v_exp_f32_e32 v54, v54
	v_exp_f32_e32 v55, v55
	v_sub_f32_e32 v56, v56, v71
	v_sub_f32_e32 v57, v57, v71
	v_exp_f32_e32 v56, v56
	v_exp_f32_e32 v57, v57
	v_sub_f32_e32 v50, v50, v71
	v_sub_f32_e32 v51, v51, v71
	v_exp_f32_e32 v50, v50
	v_exp_f32_e32 v51, v51
	v_sub_f32_e32 v52, v52, v71
	v_sub_f32_e32 v53, v53, v71
	v_exp_f32_e32 v52, v52
	v_exp_f32_e32 v53, v53
	v_pk_add_f32 v[94:95], v[54:55], 0 op_sel_hi:[1,0]
	v_sub_f32_e32 v42, v42, v71
	v_pk_add_f32 v[94:95], v[56:57], v[94:95]
	v_sub_f32_e32 v46, v46, v71
	v_sub_f32_e32 v47, v47, v71
	v_exp_f32_e32 v96, v42
	v_sub_f32_e32 v42, v43, v71
	v_pk_add_f32 v[94:95], v[50:51], v[94:95]
	v_exp_f32_e32 v46, v46
	v_exp_f32_e32 v47, v47
	v_sub_f32_e32 v48, v48, v71
	v_sub_f32_e32 v49, v49, v71
	v_exp_f32_e32 v97, v42
	v_sub_f32_e32 v42, v44, v71
	v_pk_add_f32 v[94:95], v[52:53], v[94:95]
	v_exp_f32_e32 v48, v48
	v_exp_f32_e32 v49, v49
	v_exp_f32_e32 v98, v42
	v_sub_f32_e32 v42, v45, v71
	v_cvt_pk_bf16_f32 v44, v50, v51
	v_cvt_pk_bf16_f32 v45, v52, v53
	ds_read_b128 v[50:53], v0 offset:8192
	v_exp_f32_e32 v99, v42
	v_pk_add_f32 v[94:95], v[46:47], v[94:95]
	v_cvt_pk_bf16_f32 v46, v46, v47
	v_pk_add_f32 v[94:95], v[48:49], v[94:95]
	v_cvt_pk_bf16_f32 v47, v48, v49
	v_pk_add_f32 v[42:43], v[96:97], v[94:95]
	v_cvt_pk_bf16_f32 v48, v96, v97
	v_pk_add_f32 v[42:43], v[98:99], v[42:43]
	v_cvt_pk_bf16_f32 v49, v98, v99
	v_add_f32_e32 v42, v42, v43
	v_add_f32_e32 v68, v68, v42
	v_cvt_pk_bf16_f32 v42, v54, v55
	v_cvt_pk_bf16_f32 v43, v56, v57
	s_addk_i32 s2, 0x4000
	s_and_b32 s0, s2, 0x4000
	s_waitcnt lgkmcnt(0)
	v_mfma_f32_16x16x32_bf16 v[2:5], v[50:53], v[42:45], v[2:5]
	ds_read_b128 v[50:53], v93 offset:8192
	s_add_i32 s0, s0, 0
	s_add_i32 s81, s81, 64
	s_waitcnt lgkmcnt(0)
	v_mfma_f32_16x16x32_bf16 v[2:5], v[50:53], v[46:49], v[2:5]
	ds_read_b128 v[50:53], v0 offset:10240
	s_addk_i32 s80, 0x7c
	s_cmp_eq_u32 s80, 0
	s_waitcnt lgkmcnt(0)
	v_mfma_f32_16x16x32_bf16 v[6:9], v[50:53], v[42:45], v[6:9]
	ds_read_b128 v[50:53], v93 offset:10240
	s_waitcnt lgkmcnt(0)
	v_mfma_f32_16x16x32_bf16 v[6:9], v[50:53], v[46:49], v[6:9]
	ds_read_b128 v[50:53], v0 offset:12288
	s_waitcnt lgkmcnt(0)
	v_mfma_f32_16x16x32_bf16 v[10:13], v[50:53], v[42:45], v[10:13]
	ds_read_b128 v[50:53], v93 offset:12288
	s_waitcnt lgkmcnt(0)
	v_mfma_f32_16x16x32_bf16 v[10:13], v[50:53], v[46:49], v[10:13]
	ds_read_b128 v[50:53], v0 offset:14336
	v_add_u32_e32 v0, s0, v75
	s_waitcnt lgkmcnt(0)
	v_mfma_f32_16x16x32_bf16 v[14:17], v[50:53], v[42:45], v[14:17]
	ds_read_b128 v[42:45], v93 offset:14336
	s_waitcnt vmcnt(3)
	ds_write_b128 v0, v[26:29]
	s_waitcnt vmcnt(2)
	ds_write_b128 v0, v[30:33] offset:4096
	v_add3_u32 v0, s0, v74, v72
	s_waitcnt lgkmcnt(2)
	v_mfma_f32_16x16x32_bf16 v[14:17], v[42:45], v[46:49], v[14:17]
	s_waitcnt vmcnt(1)
	ds_write_b128 v0, v[34:37] offset:8192
	s_waitcnt vmcnt(0)
	ds_write_b128 v0, v[38:41] offset:12288
	s_cbranch_scc1 .LBB0_490
	s_mov_b32 s0, s70
	s_branch .LBB0_408
.LBB0_448:
	s_mov_b64 s[4:5], 0
